# correctness hardening: s_waitcnt vmcnt(0) restored for all waves before P6 epilogue part 3 (the final_gain loads were only covered by the wait removed with the counter protocol); no timing change expe
# baseline (speedup 1.0000x reference)
.LBB0_565:
	s_waitcnt vmcnt(0) lgkmcnt(0)
	s_barrier
	v_lshl_add_u32 v245, v194, 2, 0
	v_add_u32_e32 v245, 0x21000, v245
	ds_read2_b32 v[228:229], v245 offset1:16
	ds_read2_b32 v[230:231], v245 offset0:32 offset1:48
	ds_read2_b32 v[232:233], v245 offset0:128 offset1:144
	ds_read2_b32 v[234:235], v245 offset0:160 offset1:176
	s_waitcnt lgkmcnt(0)
	v_mov_b32_e32 v242, v195
	v_lshl_add_u32 v242, v242, 13, v156
	v_pk_mul_f32 v[140:141], v[140:141], v[228:229] op_sel_hi:[1,0]
	v_pk_mul_f32 v[142:143], v[142:143], v[228:229] op_sel_hi:[1,0]
	v_pk_mul_f32 v[140:141], v[140:141], v[212:213]
	v_pk_mul_f32 v[142:143], v[142:143], v[214:215]
	global_store_dwordx4 v242, v[140:143], s[60:61]
	v_pk_mul_f32 v[136:137], v[136:137], v[228:229] op_sel_hi:[1,0]
	v_pk_mul_f32 v[138:139], v[138:139], v[228:229] op_sel_hi:[1,0]
	v_pk_mul_f32 v[136:137], v[136:137], v[216:217]
	v_pk_mul_f32 v[138:139], v[138:139], v[218:219]
	global_store_dwordx4 v242, v[136:139], s[60:61] offset:64
	v_pk_mul_f32 v[132:133], v[132:133], v[228:229] op_sel_hi:[1,0]
	v_pk_mul_f32 v[134:135], v[134:135], v[228:229] op_sel_hi:[1,0]
	v_pk_mul_f32 v[132:133], v[132:133], v[220:221]
	v_pk_mul_f32 v[134:135], v[134:135], v[222:223]
	global_store_dwordx4 v242, v[132:135], s[60:61] offset:512
	v_pk_mul_f32 v[128:129], v[128:129], v[228:229] op_sel_hi:[1,0]
	v_pk_mul_f32 v[130:131], v[130:131], v[228:229] op_sel_hi:[1,0]
	v_pk_mul_f32 v[128:129], v[128:129], v[224:225]
	v_pk_mul_f32 v[130:131], v[130:131], v[226:227]
	global_store_dwordx4 v242, v[128:131], s[60:61] offset:576
	v_add_u32_e32 v242, 16, v195
	v_lshl_add_u32 v242, v242, 13, v156
	v_pk_mul_f32 v[124:125], v[124:125], v[228:229] op_sel:[0,1] op_sel_hi:[1,1]
	v_pk_mul_f32 v[126:127], v[126:127], v[228:229] op_sel:[0,1] op_sel_hi:[1,1]
	v_pk_mul_f32 v[124:125], v[124:125], v[212:213]
	v_pk_mul_f32 v[126:127], v[126:127], v[214:215]
	global_store_dwordx4 v242, v[124:127], s[60:61]
	v_pk_mul_f32 v[120:121], v[120:121], v[228:229] op_sel:[0,1] op_sel_hi:[1,1]
	v_pk_mul_f32 v[122:123], v[122:123], v[228:229] op_sel:[0,1] op_sel_hi:[1,1]
	v_pk_mul_f32 v[120:121], v[120:121], v[216:217]
	v_pk_mul_f32 v[122:123], v[122:123], v[218:219]
	global_store_dwordx4 v242, v[120:123], s[60:61] offset:64
	v_pk_mul_f32 v[116:117], v[116:117], v[228:229] op_sel:[0,1] op_sel_hi:[1,1]
	v_pk_mul_f32 v[118:119], v[118:119], v[228:229] op_sel:[0,1] op_sel_hi:[1,1]
	v_pk_mul_f32 v[116:117], v[116:117], v[220:221]
	v_pk_mul_f32 v[118:119], v[118:119], v[222:223]
	global_store_dwordx4 v242, v[116:119], s[60:61] offset:512
	v_pk_mul_f32 v[112:113], v[112:113], v[228:229] op_sel:[0,1] op_sel_hi:[1,1]
	v_pk_mul_f32 v[114:115], v[114:115], v[228:229] op_sel:[0,1] op_sel_hi:[1,1]
	v_pk_mul_f32 v[112:113], v[112:113], v[224:225]
	v_pk_mul_f32 v[114:115], v[114:115], v[226:227]
	global_store_dwordx4 v242, v[112:115], s[60:61] offset:576
	v_add_u32_e32 v242, 32, v195
	v_lshl_add_u32 v242, v242, 13, v156
	v_pk_mul_f32 v[92:93], v[92:93], v[230:231] op_sel_hi:[1,0]
	v_pk_mul_f32 v[94:95], v[94:95], v[230:231] op_sel_hi:[1,0]
	v_pk_mul_f32 v[92:93], v[92:93], v[212:213]
	v_pk_mul_f32 v[94:95], v[94:95], v[214:215]
	global_store_dwordx4 v242, v[92:95], s[60:61]
	v_pk_mul_f32 v[88:89], v[88:89], v[230:231] op_sel_hi:[1,0]
	v_pk_mul_f32 v[90:91], v[90:91], v[230:231] op_sel_hi:[1,0]
	v_pk_mul_f32 v[88:89], v[88:89], v[216:217]
	v_pk_mul_f32 v[90:91], v[90:91], v[218:219]
	global_store_dwordx4 v242, v[88:91], s[60:61] offset:64
	v_pk_mul_f32 v[84:85], v[84:85], v[230:231] op_sel_hi:[1,0]
	v_pk_mul_f32 v[86:87], v[86:87], v[230:231] op_sel_hi:[1,0]
	v_pk_mul_f32 v[84:85], v[84:85], v[220:221]
	v_pk_mul_f32 v[86:87], v[86:87], v[222:223]
	global_store_dwordx4 v242, v[84:87], s[60:61] offset:512
	v_pk_mul_f32 v[80:81], v[80:81], v[230:231] op_sel_hi:[1,0]
	v_pk_mul_f32 v[82:83], v[82:83], v[230:231] op_sel_hi:[1,0]
	v_pk_mul_f32 v[80:81], v[80:81], v[224:225]
	v_pk_mul_f32 v[82:83], v[82:83], v[226:227]
	global_store_dwordx4 v242, v[80:83], s[60:61] offset:576
	v_add_u32_e32 v242, 48, v195
	v_lshl_add_u32 v242, v242, 13, v156
	v_pk_mul_f32 v[76:77], v[76:77], v[230:231] op_sel:[0,1] op_sel_hi:[1,1]
	v_pk_mul_f32 v[78:79], v[78:79], v[230:231] op_sel:[0,1] op_sel_hi:[1,1]
	v_pk_mul_f32 v[76:77], v[76:77], v[212:213]
	v_pk_mul_f32 v[78:79], v[78:79], v[214:215]
	global_store_dwordx4 v242, v[76:79], s[60:61]
	v_pk_mul_f32 v[72:73], v[72:73], v[230:231] op_sel:[0,1] op_sel_hi:[1,1]
	v_pk_mul_f32 v[74:75], v[74:75], v[230:231] op_sel:[0,1] op_sel_hi:[1,1]
	v_pk_mul_f32 v[72:73], v[72:73], v[216:217]
	v_pk_mul_f32 v[74:75], v[74:75], v[218:219]
	global_store_dwordx4 v242, v[72:75], s[60:61] offset:64
	v_pk_mul_f32 v[68:69], v[68:69], v[230:231] op_sel:[0,1] op_sel_hi:[1,1]
	v_pk_mul_f32 v[70:71], v[70:71], v[230:231] op_sel:[0,1] op_sel_hi:[1,1]
	v_pk_mul_f32 v[68:69], v[68:69], v[220:221]
	v_pk_mul_f32 v[70:71], v[70:71], v[222:223]
	global_store_dwordx4 v242, v[68:71], s[60:61] offset:512
	v_pk_mul_f32 v[64:65], v[64:65], v[230:231] op_sel:[0,1] op_sel_hi:[1,1]
	v_pk_mul_f32 v[66:67], v[66:67], v[230:231] op_sel:[0,1] op_sel_hi:[1,1]
	v_pk_mul_f32 v[64:65], v[64:65], v[224:225]
	v_pk_mul_f32 v[66:67], v[66:67], v[226:227]
	global_store_dwordx4 v242, v[64:67], s[60:61] offset:576
	v_add_u32_e32 v242, 128, v195
	v_lshl_add_u32 v242, v242, 13, v156
	v_pk_mul_f32 v[60:61], v[60:61], v[232:233] op_sel_hi:[1,0]
	v_pk_mul_f32 v[62:63], v[62:63], v[232:233] op_sel_hi:[1,0]
	v_pk_mul_f32 v[60:61], v[60:61], v[212:213]
	v_pk_mul_f32 v[62:63], v[62:63], v[214:215]
	global_store_dwordx4 v242, v[60:63], s[60:61]
	v_pk_mul_f32 v[56:57], v[56:57], v[232:233] op_sel_hi:[1,0]
	v_pk_mul_f32 v[58:59], v[58:59], v[232:233] op_sel_hi:[1,0]
	v_pk_mul_f32 v[56:57], v[56:57], v[216:217]
	v_pk_mul_f32 v[58:59], v[58:59], v[218:219]
	global_store_dwordx4 v242, v[56:59], s[60:61] offset:64
	v_pk_mul_f32 v[52:53], v[52:53], v[232:233] op_sel_hi:[1,0]
	v_pk_mul_f32 v[54:55], v[54:55], v[232:233] op_sel_hi:[1,0]
	v_pk_mul_f32 v[52:53], v[52:53], v[220:221]
	v_pk_mul_f32 v[54:55], v[54:55], v[222:223]
	global_store_dwordx4 v242, v[52:55], s[60:61] offset:512
	v_pk_mul_f32 v[48:49], v[48:49], v[232:233] op_sel_hi:[1,0]
	v_pk_mul_f32 v[50:51], v[50:51], v[232:233] op_sel_hi:[1,0]
	v_pk_mul_f32 v[48:49], v[48:49], v[224:225]
	v_pk_mul_f32 v[50:51], v[50:51], v[226:227]
	global_store_dwordx4 v242, v[48:51], s[60:61] offset:576
	v_add_u32_e32 v242, 144, v195
	v_lshl_add_u32 v242, v242, 13, v156
	v_pk_mul_f32 v[44:45], v[44:45], v[232:233] op_sel:[0,1] op_sel_hi:[1,1]
	v_pk_mul_f32 v[46:47], v[46:47], v[232:233] op_sel:[0,1] op_sel_hi:[1,1]
	v_pk_mul_f32 v[44:45], v[44:45], v[212:213]
	v_pk_mul_f32 v[46:47], v[46:47], v[214:215]
	global_store_dwordx4 v242, v[44:47], s[60:61]
	v_pk_mul_f32 v[40:41], v[40:41], v[232:233] op_sel:[0,1] op_sel_hi:[1,1]
	v_pk_mul_f32 v[42:43], v[42:43], v[232:233] op_sel:[0,1] op_sel_hi:[1,1]
	v_pk_mul_f32 v[40:41], v[40:41], v[216:217]
	v_pk_mul_f32 v[42:43], v[42:43], v[218:219]
	global_store_dwordx4 v242, v[40:43], s[60:61] offset:64
	v_pk_mul_f32 v[36:37], v[36:37], v[232:233] op_sel:[0,1] op_sel_hi:[1,1]
	v_pk_mul_f32 v[38:39], v[38:39], v[232:233] op_sel:[0,1] op_sel_hi:[1,1]
	v_pk_mul_f32 v[36:37], v[36:37], v[220:221]
	v_pk_mul_f32 v[38:39], v[38:39], v[222:223]
	global_store_dwordx4 v242, v[36:39], s[60:61] offset:512
	v_pk_mul_f32 v[32:33], v[32:33], v[232:233] op_sel:[0,1] op_sel_hi:[1,1]
	v_pk_mul_f32 v[34:35], v[34:35], v[232:233] op_sel:[0,1] op_sel_hi:[1,1]
	v_pk_mul_f32 v[32:33], v[32:33], v[224:225]
	v_pk_mul_f32 v[34:35], v[34:35], v[226:227]
	global_store_dwordx4 v242, v[32:35], s[60:61] offset:576
	v_add_u32_e32 v242, 160, v195
	v_lshl_add_u32 v242, v242, 13, v156
	v_pk_mul_f32 v[28:29], v[28:29], v[234:235] op_sel_hi:[1,0]
	v_pk_mul_f32 v[30:31], v[30:31], v[234:235] op_sel_hi:[1,0]
	v_pk_mul_f32 v[28:29], v[28:29], v[212:213]
	v_pk_mul_f32 v[30:31], v[30:31], v[214:215]
	global_store_dwordx4 v242, v[28:31], s[60:61]
	v_pk_mul_f32 v[24:25], v[24:25], v[234:235] op_sel_hi:[1,0]
	v_pk_mul_f32 v[26:27], v[26:27], v[234:235] op_sel_hi:[1,0]
	v_pk_mul_f32 v[24:25], v[24:25], v[216:217]
	v_pk_mul_f32 v[26:27], v[26:27], v[218:219]
	global_store_dwordx4 v242, v[24:27], s[60:61] offset:64
	v_pk_mul_f32 v[20:21], v[20:21], v[234:235] op_sel_hi:[1,0]
	v_pk_mul_f32 v[22:23], v[22:23], v[234:235] op_sel_hi:[1,0]
	v_pk_mul_f32 v[20:21], v[20:21], v[220:221]
	v_pk_mul_f32 v[22:23], v[22:23], v[222:223]
	global_store_dwordx4 v242, v[20:23], s[60:61] offset:512
	v_pk_mul_f32 v[16:17], v[16:17], v[234:235] op_sel_hi:[1,0]
	v_pk_mul_f32 v[18:19], v[18:19], v[234:235] op_sel_hi:[1,0]
	v_pk_mul_f32 v[16:17], v[16:17], v[224:225]
	v_pk_mul_f32 v[18:19], v[18:19], v[226:227]
	global_store_dwordx4 v242, v[16:19], s[60:61] offset:576
	v_add_u32_e32 v242, 176, v195
	v_lshl_add_u32 v242, v242, 13, v156
	v_pk_mul_f32 v[12:13], v[12:13], v[234:235] op_sel:[0,1] op_sel_hi:[1,1]
	v_pk_mul_f32 v[14:15], v[14:15], v[234:235] op_sel:[0,1] op_sel_hi:[1,1]
	v_pk_mul_f32 v[12:13], v[12:13], v[212:213]
	v_pk_mul_f32 v[14:15], v[14:15], v[214:215]
	global_store_dwordx4 v242, v[12:15], s[60:61]
	v_pk_mul_f32 v[8:9], v[8:9], v[234:235] op_sel:[0,1] op_sel_hi:[1,1]
	v_pk_mul_f32 v[10:11], v[10:11], v[234:235] op_sel:[0,1] op_sel_hi:[1,1]
	v_pk_mul_f32 v[8:9], v[8:9], v[216:217]
	v_pk_mul_f32 v[10:11], v[10:11], v[218:219]
	global_store_dwordx4 v242, v[8:11], s[60:61] offset:64
	v_pk_mul_f32 v[4:5], v[4:5], v[234:235] op_sel:[0,1] op_sel_hi:[1,1]
	v_pk_mul_f32 v[6:7], v[6:7], v[234:235] op_sel:[0,1] op_sel_hi:[1,1]
	v_pk_mul_f32 v[4:5], v[4:5], v[220:221]
	v_pk_mul_f32 v[6:7], v[6:7], v[222:223]
	global_store_dwordx4 v242, v[4:7], s[60:61] offset:512
	v_pk_mul_f32 v[0:1], v[0:1], v[234:235] op_sel:[0,1] op_sel_hi:[1,1]
	v_pk_mul_f32 v[2:3], v[2:3], v[234:235] op_sel:[0,1] op_sel_hi:[1,1]
	v_pk_mul_f32 v[0:1], v[0:1], v[224:225]
	v_pk_mul_f32 v[2:3], v[2:3], v[226:227]
	global_store_dwordx4 v242, v[0:3], s[60:61] offset:576
	s_mov_b64 s[2:3], -1
	s_cmp_eq_u32 s66, 3
	s_cbranch_scc1 .LBB0_527
	s_andn2_b64 vcc, exec, s[8:9]
	s_cbranch_vccnz .LBB0_526
	s_barrier
	s_branch .LBB0_526
